# grid barrier: all waiters poll the top-level arrival counter (>= target) instead of a separate generation word bumped after the last arrival returns
# baseline (speedup 1.0000x reference)
.LBB0_1163:
	s_or_b64 exec, exec, s[4:5]
	v_cvt_f32_u32_e32 v4, v2
	s_waitcnt vmcnt(0)
	v_readfirstlane_b32 s2, v3
	v_sub_u32_e32 v3, 0, v2
	v_rcp_iflag_f32_e32 v4, v4
	v_add_u32_e32 v5, s2, v1
	v_mul_f32_e32 v4, 0x4f7ffffe, v4
	v_cvt_u32_f32_e32 v4, v4
	v_mul_lo_u32 v1, v3, v4
	v_mul_hi_u32 v1, v4, v1
	v_add_u32_e32 v1, v4, v1
	v_mul_hi_u32 v1, v5, v1
	v_mul_lo_u32 v3, v1, v2
	v_sub_u32_e32 v3, v5, v3
	v_add_u32_e32 v4, 1, v1
	v_cmp_ge_u32_e32 vcc, v3, v2
	s_nop 1
	v_cndmask_b32_e32 v1, v1, v4, vcc
	v_sub_u32_e32 v4, v3, v2
	v_cndmask_b32_e32 v3, v3, v4, vcc
	v_add_u32_e32 v4, 1, v1
	v_cmp_ge_u32_e32 vcc, v3, v2
	v_add_u32_e32 v3, 1, v5
	s_nop 0
	v_cndmask_b32_e32 v1, v1, v4, vcc
	v_mul_lo_u32 v4, v2, v1
	v_add_u32_e32 v2, v4, v2
	v_cmp_ne_u32_e32 vcc, v3, v2
	s_and_saveexec_b64 s[4:5], vcc
	s_xor_b64 s[4:5], exec, s[4:5]
	s_cbranch_execz .LBB0_1177
	v_readlane_b32 s6, v255, 17
	v_readlane_b32 s7, v255, 18
	s_waitcnt lgkmcnt(0)
	v_add_u32_e32 v1, 1, v1
	v_mul_lo_u32 v1, v1, v0
	s_nop 3
	global_load_dword v0, v173, s[6:7] sc1
	s_waitcnt vmcnt(0)
	v_cmp_lt_u32_e32 vcc, v0, v1
	s_and_saveexec_b64 s[6:7], vcc
	s_cbranch_execz .LBB0_1176
	s_mov_b32 s2, 1
	s_mov_b64 s[8:9], 0
	s_branch .LBB0_1167

.LBB0_1171:
	v_readlane_b32 s26, v255, 17
	v_readlane_b32 s27, v255, 18
	s_add_i32 s2, s2, 1
	s_mov_b64 s[28:29], -1
	s_nop 2
	global_load_dword v0, v173, s[26:27] sc1
	s_waitcnt vmcnt(0)
	v_cmp_ge_u32_e32 vcc, v0, v1
	s_orn2_b64 s[26:27], vcc, exec
	s_branch .LBB0_1166

.LBB0_1180:
	s_or_b64 exec, exec, s[6:7]
	s_waitcnt vmcnt(0)
	v_readfirstlane_b32 s2, v2
	v_cvt_f32_u32_e32 v2, v0
	v_sub_u32_e32 v3, 0, v0
	v_add_u32_e32 v1, s2, v1
	v_readlane_b32 s4, v255, 19
	v_rcp_iflag_f32_e32 v2, v2
	v_readlane_b32 s5, v255, 20
	s_mov_b64 s[6:7], -1
	v_mul_f32_e32 v2, 0x4f7ffffe, v2
	v_cvt_u32_f32_e32 v2, v2
	v_mul_lo_u32 v3, v3, v2
	v_mul_hi_u32 v3, v2, v3
	v_add_u32_e32 v2, v2, v3
	v_mul_hi_u32 v2, v1, v2
	v_mul_lo_u32 v3, v2, v0
	v_sub_u32_e32 v3, v1, v3
	v_cmp_ge_u32_e32 vcc, v3, v0
	v_add_u32_e32 v4, 1, v2
	v_add_u32_e32 v1, 1, v1
	v_cndmask_b32_e32 v2, v2, v4, vcc
	v_sub_u32_e32 v4, v3, v0
	v_cndmask_b32_e32 v3, v3, v4, vcc
	v_cmp_ge_u32_e32 vcc, v3, v0
	v_add_u32_e32 v3, 1, v2
	s_nop 0
	v_cndmask_b32_e32 v2, v2, v3, vcc
	v_mul_lo_u32 v3, v0, v2
	v_add_u32_e32 v0, v3, v0
	v_mov_b32_e32 v6, v0
	v_cmp_ne_u32_e32 vcc, v1, v0
	v_mov_b64_e32 v[0:1], s[4:5]
	s_and_saveexec_b64 s[4:5], vcc
	s_cbranch_execz .LBB0_1193
	v_readlane_b32 s6, v255, 17
	v_readlane_b32 s7, v255, 18
	s_mov_b64 s[8:9], 0
	s_nop 3
	global_load_dword v0, v173, s[6:7] sc1
	s_waitcnt vmcnt(0)
	v_cmp_lt_u32_e32 vcc, v0, v6
	s_and_saveexec_b64 s[6:7], vcc
	s_cbranch_execz .LBB0_1192
	s_mov_b32 s2, 1
	s_branch .LBB0_1184

.LBB0_1188:
	v_readlane_b32 s26, v255, 17
	v_readlane_b32 s27, v255, 18
	s_add_i32 s2, s2, 1
	s_mov_b64 s[28:29], -1
	s_nop 2
	global_load_dword v0, v173, s[26:27] sc1
	s_waitcnt vmcnt(0)
	v_cmp_ge_u32_e32 vcc, v0, v6
	s_orn2_b64 s[26:27], vcc, exec
	s_branch .LBB0_1183
